# sample-path sgemm units: cross-wave reduce loop issues its four LDS reads together (same summation order)
# speedup vs baseline: 1.0028x; 1.0028x over previous
.LBB0_178:
	v_ashrrev_i32_e32 v1, 10, v0
	v_and_b32_e32 v2, 0x3ff, v0
	v_lshlrev_b32_e32 v3, 16, v1
	v_lshlrev_b32_e32 v2, 2, v2
	v_add3_u32 v4, 0, v3, v2
	ds_read2st64_b32 v[2:3], v4 offset0:128 offset1:144
	ds_read2st64_b32 v[6:7], v4 offset0:160 offset1:176
	ds_read2st64_b32 v[8:9], v4 offset0:192 offset1:208
	ds_read2st64_b32 v[10:11], v4 offset0:224 offset1:240
	v_cmp_lt_i32_e32 vcc, s13, v0
	s_or_b64 s[2:3], vcc, s[2:3]
	v_mov_b32_e32 v4, s27
	v_mad_i32_i24 v1, v1, s14, v4
	s_waitcnt lgkmcnt(3)
	v_add_f32_e32 v2, 0, v2
	v_add_f32_e32 v5, v2, v3
	s_waitcnt lgkmcnt(2)
	v_add_f32_e32 v2, v5, v6
	v_add_f32_e32 v5, v2, v7
	s_waitcnt lgkmcnt(1)
	v_add_f32_e32 v2, v5, v8
	v_add_f32_e32 v5, v2, v9
	s_waitcnt lgkmcnt(0)
	v_add_f32_e32 v2, v5, v10
	v_add_f32_e32 v2, v2, v11
	v_bfe_u32 v3, v0, 5, 5
	v_mul_u32_u24_e32 v3, 0x84, v3
	v_add3_u32 v1, v1, v3, v79
	ds_write_b32 v1, v2
	v_add_u32_e32 v1, 0x200, v0
	v_mov_b32_e32 v0, v1
	s_andn2_b64 exec, exec, s[2:3]
	s_cbranch_execnz .LBB0_178

.LBB0_280:
	v_ashrrev_i32_e32 v1, 10, v0
	v_and_b32_e32 v2, 0x3ff, v0
	v_lshlrev_b32_e32 v3, 16, v1
	v_lshlrev_b32_e32 v2, 2, v2
	v_add3_u32 v4, 0, v3, v2
	ds_read2st64_b32 v[2:3], v4 offset0:128 offset1:144
	ds_read2st64_b32 v[6:7], v4 offset0:160 offset1:176
	ds_read2st64_b32 v[8:9], v4 offset0:192 offset1:208
	ds_read2st64_b32 v[10:11], v4 offset0:224 offset1:240
	v_cmp_lt_i32_e32 vcc, s12, v0
	s_or_b64 s[2:3], vcc, s[2:3]
	v_mov_b32_e32 v4, s27
	v_mad_i32_i24 v1, v1, s28, v4
	s_waitcnt lgkmcnt(3)
	v_add_f32_e32 v2, 0, v2
	v_add_f32_e32 v5, v2, v3
	s_waitcnt lgkmcnt(2)
	v_add_f32_e32 v2, v5, v6
	v_add_f32_e32 v5, v2, v7
	s_waitcnt lgkmcnt(1)
	v_add_f32_e32 v2, v5, v8
	v_add_f32_e32 v5, v2, v9
	s_waitcnt lgkmcnt(0)
	v_add_f32_e32 v2, v5, v10
	v_add_f32_e32 v2, v2, v11
	v_bfe_u32 v3, v0, 5, 5
	v_mul_u32_u24_e32 v3, 0x84, v3
	v_add3_u32 v1, v1, v3, v79
	ds_write_b32 v1, v2
	v_add_u32_e32 v1, 0x200, v0
	v_mov_b32_e32 v0, v1
	s_andn2_b64 exec, exec, s[2:3]
	s_cbranch_execnz .LBB0_280

.LBB0_1257:
	v_ashrrev_i32_e32 v1, 10, v0
	v_and_b32_e32 v2, 0x3ff, v0
	v_lshlrev_b32_e32 v3, 16, v1
	v_lshlrev_b32_e32 v2, 2, v2
	v_add3_u32 v4, 0, v3, v2
	ds_read2st64_b32 v[2:3], v4 offset0:128 offset1:144
	ds_read2st64_b32 v[6:7], v4 offset0:160 offset1:176
	ds_read2st64_b32 v[8:9], v4 offset0:192 offset1:208
	ds_read2st64_b32 v[10:11], v4 offset0:224 offset1:240
	v_cmp_lt_i32_e32 vcc, s30, v0
	s_or_b64 s[2:3], vcc, s[2:3]
	v_mov_b32_e32 v4, s27
	v_mad_i32_i24 v1, v1, s31, v4
	s_waitcnt lgkmcnt(3)
	v_add_f32_e32 v2, 0, v2
	v_add_f32_e32 v5, v2, v3
	s_waitcnt lgkmcnt(2)
	v_add_f32_e32 v2, v5, v6
	v_add_f32_e32 v5, v2, v7
	s_waitcnt lgkmcnt(1)
	v_add_f32_e32 v2, v5, v8
	v_add_f32_e32 v5, v2, v9
	s_waitcnt lgkmcnt(0)
	v_add_f32_e32 v2, v5, v10
	v_add_f32_e32 v2, v2, v11
	v_bfe_u32 v3, v0, 5, 5
	v_mul_u32_u24_e32 v3, 0x84, v3
	v_add3_u32 v1, v1, v3, v83
	ds_write_b32 v1, v2
	v_add_u32_e32 v1, 0x200, v0
	v_mov_b32_e32 v0, v1
	s_andn2_b64 exec, exec, s[2:3]
	s_cbranch_execnz .LBB0_1257

.LBB0_1340:
	v_ashrrev_i32_e32 v1, 10, v0
	v_and_b32_e32 v2, 0x3ff, v0
	v_lshlrev_b32_e32 v3, 16, v1
	v_lshlrev_b32_e32 v2, 2, v2
	v_add3_u32 v4, 0, v3, v2
	ds_read2st64_b32 v[2:3], v4 offset0:128 offset1:144
	ds_read2st64_b32 v[6:7], v4 offset0:160 offset1:176
	ds_read2st64_b32 v[8:9], v4 offset0:192 offset1:208
	ds_read2st64_b32 v[10:11], v4 offset0:224 offset1:240
	v_cmp_lt_i32_e32 vcc, s41, v0
	s_or_b64 s[2:3], vcc, s[2:3]
	v_mov_b32_e32 v4, s27
	v_mad_i32_i24 v1, v1, s42, v4
	s_waitcnt lgkmcnt(3)
	v_add_f32_e32 v2, 0, v2
	v_add_f32_e32 v5, v2, v3
	s_waitcnt lgkmcnt(2)
	v_add_f32_e32 v2, v5, v6
	v_add_f32_e32 v5, v2, v7
	s_waitcnt lgkmcnt(1)
	v_add_f32_e32 v2, v5, v8
	v_add_f32_e32 v5, v2, v9
	s_waitcnt lgkmcnt(0)
	v_add_f32_e32 v2, v5, v10
	v_add_f32_e32 v2, v2, v11
	v_bfe_u32 v3, v0, 5, 5
	v_mul_u32_u24_e32 v3, 0x84, v3
	v_add3_u32 v1, v1, v3, v83
	ds_write_b32 v1, v2
	v_add_u32_e32 v1, 0x200, v0
	v_mov_b32_e32 v0, v1
	s_andn2_b64 exec, exec, s[2:3]
	s_cbranch_execnz .LBB0_1340

.LBB0_2058:
	v_ashrrev_i32_e32 v1, 10, v0
	v_and_b32_e32 v2, 0x3ff, v0
	v_lshlrev_b32_e32 v3, 16, v1
	v_lshlrev_b32_e32 v2, 2, v2
	v_add3_u32 v4, 0, v3, v2
	ds_read2st64_b32 v[2:3], v4 offset0:128 offset1:144
	ds_read2st64_b32 v[6:7], v4 offset0:160 offset1:176
	ds_read2st64_b32 v[8:9], v4 offset0:192 offset1:208
	ds_read2st64_b32 v[10:11], v4 offset0:224 offset1:240
	v_cmp_lt_i32_e32 vcc, s20, v0
	s_or_b64 s[2:3], vcc, s[2:3]
	v_mov_b32_e32 v4, s27
	v_mad_i32_i24 v1, v1, s21, v4
	s_waitcnt lgkmcnt(3)
	v_add_f32_e32 v2, 0, v2
	v_add_f32_e32 v5, v2, v3
	s_waitcnt lgkmcnt(2)
	v_add_f32_e32 v2, v5, v6
	v_add_f32_e32 v5, v2, v7
	s_waitcnt lgkmcnt(1)
	v_add_f32_e32 v2, v5, v8
	v_add_f32_e32 v5, v2, v9
	s_waitcnt lgkmcnt(0)
	v_add_f32_e32 v2, v5, v10
	v_add_f32_e32 v2, v2, v11
	v_bfe_u32 v3, v0, 5, 5
	v_mul_u32_u24_e32 v3, 0x84, v3
	v_add3_u32 v1, v1, v3, v83
	ds_write_b32 v1, v2
	v_add_u32_e32 v1, 0x200, v0
	v_mov_b32_e32 v0, v1
	s_andn2_b64 exec, exec, s[2:3]
	s_cbranch_execnz .LBB0_2058

.LBB0_2335:
	v_ashrrev_i32_e32 v1, 10, v0
	v_and_b32_e32 v2, 0x3ff, v0
	v_lshlrev_b32_e32 v3, 16, v1
	v_lshlrev_b32_e32 v2, 2, v2
	v_add3_u32 v4, 0, v3, v2
	ds_read2st64_b32 v[2:3], v4 offset0:128 offset1:144
	ds_read2st64_b32 v[6:7], v4 offset0:160 offset1:176
	ds_read2st64_b32 v[8:9], v4 offset0:192 offset1:208
	ds_read2st64_b32 v[10:11], v4 offset0:224 offset1:240
	v_cmp_lt_i32_e32 vcc, s44, v0
	s_or_b64 s[2:3], vcc, s[2:3]
	v_mov_b32_e32 v4, s27
	v_mad_i32_i24 v1, v1, s31, v4
	s_waitcnt lgkmcnt(3)
	v_add_f32_e32 v2, 0, v2
	v_add_f32_e32 v5, v2, v3
	s_waitcnt lgkmcnt(2)
	v_add_f32_e32 v2, v5, v6
	v_add_f32_e32 v5, v2, v7
	s_waitcnt lgkmcnt(1)
	v_add_f32_e32 v2, v5, v8
	v_add_f32_e32 v5, v2, v9
	s_waitcnt lgkmcnt(0)
	v_add_f32_e32 v2, v5, v10
	v_add_f32_e32 v2, v2, v11
	v_bfe_u32 v3, v0, 5, 5
	v_mul_u32_u24_e32 v3, 0x84, v3
	v_add3_u32 v1, v1, v3, v81
	ds_write_b32 v1, v2
	v_add_u32_e32 v1, 0x200, v0
	v_mov_b32_e32 v0, v1
	s_andn2_b64 exec, exec, s[2:3]
	s_cbranch_execnz .LBB0_2335
	s_branch .LBB0_2332

.LBB0_2439:
	v_ashrrev_i32_e32 v1, 10, v0
	v_and_b32_e32 v2, 0x3ff, v0
	v_lshlrev_b32_e32 v3, 16, v1
	v_lshlrev_b32_e32 v2, 2, v2
	v_add3_u32 v4, 0, v3, v2
	ds_read2st64_b32 v[2:3], v4 offset0:128 offset1:144
	ds_read2st64_b32 v[6:7], v4 offset0:160 offset1:176
	ds_read2st64_b32 v[8:9], v4 offset0:192 offset1:208
	ds_read2st64_b32 v[10:11], v4 offset0:224 offset1:240
	v_cmp_lt_i32_e32 vcc, s35, v0
	s_or_b64 s[2:3], vcc, s[2:3]
	v_mov_b32_e32 v4, s27
	v_mad_i32_i24 v1, v1, s31, v4
	s_waitcnt lgkmcnt(3)
	v_add_f32_e32 v2, 0, v2
	v_add_f32_e32 v5, v2, v3
	s_waitcnt lgkmcnt(2)
	v_add_f32_e32 v2, v5, v6
	v_add_f32_e32 v5, v2, v7
	s_waitcnt lgkmcnt(1)
	v_add_f32_e32 v2, v5, v8
	v_add_f32_e32 v5, v2, v9
	s_waitcnt lgkmcnt(0)
	v_add_f32_e32 v2, v5, v10
	v_add_f32_e32 v2, v2, v11
	v_bfe_u32 v3, v0, 5, 5
	v_mul_u32_u24_e32 v3, 0x84, v3
	v_add3_u32 v1, v1, v3, v81
	ds_write_b32 v1, v2
	v_add_u32_e32 v1, 0x200, v0
	v_mov_b32_e32 v0, v1
	s_andn2_b64 exec, exec, s[2:3]
	s_cbranch_execnz .LBB0_2439
	s_branch .LBB0_2436

.LBB0_2659:
	v_ashrrev_i32_e32 v1, 10, v0
	v_and_b32_e32 v2, 0x3ff, v0
	v_lshlrev_b32_e32 v3, 16, v1
	v_lshlrev_b32_e32 v2, 2, v2
	v_add3_u32 v4, 0, v3, v2
	ds_read2st64_b32 v[2:3], v4 offset0:128 offset1:144
	ds_read2st64_b32 v[6:7], v4 offset0:160 offset1:176
	ds_read2st64_b32 v[8:9], v4 offset0:192 offset1:208
	ds_read2st64_b32 v[10:11], v4 offset0:224 offset1:240
	v_cmp_lt_i32_e32 vcc, s20, v0
	s_or_b64 s[2:3], vcc, s[2:3]
	v_mov_b32_e32 v4, s27
	v_mad_i32_i24 v1, v1, s29, v4
	s_waitcnt lgkmcnt(3)
	v_add_f32_e32 v2, 0, v2
	v_add_f32_e32 v5, v2, v3
	s_waitcnt lgkmcnt(2)
	v_add_f32_e32 v2, v5, v6
	v_add_f32_e32 v5, v2, v7
	s_waitcnt lgkmcnt(1)
	v_add_f32_e32 v2, v5, v8
	v_add_f32_e32 v5, v2, v9
	s_waitcnt lgkmcnt(0)
	v_add_f32_e32 v2, v5, v10
	v_add_f32_e32 v2, v2, v11
	v_bfe_u32 v3, v0, 5, 5
	v_mul_u32_u24_e32 v3, 0x84, v3
	v_add3_u32 v1, v1, v3, v203
	ds_write_b32 v1, v2
	v_add_u32_e32 v1, 0x200, v0
	v_mov_b32_e32 v0, v1
	s_andn2_b64 exec, exec, s[2:3]
	s_cbranch_execnz .LBB0_2659

.LBB0_2757:
	v_ashrrev_i32_e32 v1, 10, v0
	v_and_b32_e32 v2, 0x3ff, v0
	v_lshlrev_b32_e32 v3, 16, v1
	v_lshlrev_b32_e32 v2, 2, v2
	v_add3_u32 v4, 0, v3, v2
	ds_read2st64_b32 v[2:3], v4 offset0:128 offset1:144
	ds_read2st64_b32 v[6:7], v4 offset0:160 offset1:176
	ds_read2st64_b32 v[8:9], v4 offset0:192 offset1:208
	ds_read2st64_b32 v[10:11], v4 offset0:224 offset1:240
	v_cmp_lt_i32_e32 vcc, s20, v0
	s_or_b64 s[2:3], vcc, s[2:3]
	v_mov_b32_e32 v4, s27
	v_mad_i32_i24 v1, v1, s36, v4
	s_waitcnt lgkmcnt(3)
	v_add_f32_e32 v2, 0, v2
	v_add_f32_e32 v5, v2, v3
	s_waitcnt lgkmcnt(2)
	v_add_f32_e32 v2, v5, v6
	v_add_f32_e32 v5, v2, v7
	s_waitcnt lgkmcnt(1)
	v_add_f32_e32 v2, v5, v8
	v_add_f32_e32 v5, v2, v9
	s_waitcnt lgkmcnt(0)
	v_add_f32_e32 v2, v5, v10
	v_add_f32_e32 v2, v2, v11
	v_bfe_u32 v3, v0, 5, 5
	v_mul_u32_u24_e32 v3, 0x84, v3
	v_add3_u32 v1, v1, v3, v203
	ds_write_b32 v1, v2
	v_add_u32_e32 v1, 0x200, v0
	v_mov_b32_e32 v0, v1
	s_andn2_b64 exec, exec, s[2:3]
	s_cbranch_execnz .LBB0_2757

.LBB0_2914:
	v_ashrrev_i32_e32 v1, 10, v0
	v_and_b32_e32 v2, 0x3ff, v0
	v_lshlrev_b32_e32 v3, 16, v1
	v_lshlrev_b32_e32 v2, 2, v2
	v_add3_u32 v4, 0, v3, v2
	ds_read2st64_b32 v[2:3], v4 offset0:128 offset1:144
	ds_read2st64_b32 v[6:7], v4 offset0:160 offset1:176
	ds_read2st64_b32 v[8:9], v4 offset0:192 offset1:208
	ds_read2st64_b32 v[10:11], v4 offset0:224 offset1:240
	v_cmp_lt_i32_e32 vcc, s0, v0
	s_or_b64 s[2:3], vcc, s[2:3]
	v_mov_b32_e32 v4, s27
	v_mad_i32_i24 v1, v1, s1, v4
	s_waitcnt lgkmcnt(3)
	v_add_f32_e32 v2, 0, v2
	v_add_f32_e32 v5, v2, v3
	s_waitcnt lgkmcnt(2)
	v_add_f32_e32 v2, v5, v6
	v_add_f32_e32 v5, v2, v7
	s_waitcnt lgkmcnt(1)
	v_add_f32_e32 v2, v5, v8
	v_add_f32_e32 v5, v2, v9
	s_waitcnt lgkmcnt(0)
	v_add_f32_e32 v2, v5, v10
	v_add_f32_e32 v2, v2, v11
	v_bfe_u32 v3, v0, 5, 5
	v_mul_u32_u24_e32 v3, 0x84, v3
	v_add3_u32 v1, v1, v3, v203
	ds_write_b32 v1, v2
	v_add_u32_e32 v1, 0x200, v0
	v_mov_b32_e32 v0, v1
	s_andn2_b64 exec, exec, s[2:3]
	s_cbranch_execnz .LBB0_2914
